# residual epilogue: bf16(h*gain) pieces of the two 32-column blocks gathered through LDS and stored as 16 B per lane (dwordx4, 16 instead of 32 stores per wave and unit), one group later
# speedup vs baseline: 1.0062x; 1.0062x over previous
.LBB0_480:
	s_and_b64 vcc, exec, s[12:13]
	s_cbranch_vccnz .Lres_orig
	v_lshrrev_b32_e32 v145, 6, v154
	v_bfe_u32 v146, v163, 5, 2
	v_lshl_add_u32 v151, s22, 2, v146
	v_lshl_add_u32 v145, v145, 2, v146
	v_mul_u32_u24_e32 v145, 2304, v145
	v_add_u32_e32 v145, 135424, v145
	v_and_b32_e32 v146, 15, v189
	v_mul_u32_u24_e32 v146, 144, v146
	v_lshrrev_b32_e32 v147, 4, v189
	v_lshl_add_u32 v146, v147, 5, v146
	v_add_u32_e32 v152, v145, v146
	v_lshrrev_b32_e32 v146, 3, v189
	v_and_b32_e32 v147, 7, v189
	v_mul_u32_u24_e32 v153, 144, v146
	v_lshl_add_u32 v153, v147, 4, v153
	v_add_u32_e32 v153, v145, v153
	v_and_b32_e32 v148, 0xfffffff0, v154
	v_add_u32_e32 v148, v148, v146
	v_lshl_add_u32 v148, s23, 8, v148
	v_and_b32_e32 v149, 0x60, v163
	v_lshl_add_u32 v149, s22, 8, v149
	v_lshlrev_b32_e32 v238, 6, v148
	v_lshl_add_u32 v238, v151, 2, v238
	v_add_u32_e32 v238, 0x4100000, v238
	v_lshl_add_u32 v150, v147, 2, v149
	v_lshlrev_b32_e32 v239, 11, v148
	v_lshl_add_u32 v239, v149, 1, v239
	v_lshrrev_b32_e32 v170, 2, v147
	v_lshl_add_u32 v239, v170, 8, v239
	v_and_b32_e32 v170, 3, v147
	v_lshl_add_u32 v239, v170, 4, v239
	v_mul_u32_u24_e32 v234, 144, v146
	v_lshl_add_u32 v234, v147, 3, v234
	v_add_u32_e32 v234, v145, v234
	v_readlane_b32 s18, v254, 27
	v_readlane_b32 s19, v254, 28
	v_readlane_b32 s20, v254, 33
	v_readlane_b32 s21, v254, 34
	v_lshlrev_b32_e32 v150, 2, v150
	s_cmp_eq_u32 s78, 6
	s_cselect_b64 s[40:41], -1, 0
	s_cmp_eq_u32 s78, 2
	s_cselect_b64 vcc, -1, 0
	s_or_b64 s[40:41], s[40:41], vcc
	s_and_b64 vcc, exec, s[40:41]
	s_cselect_b32 s40, s18, s20
	s_cselect_b32 s41, s19, s21
	global_load_dwordx4 v[224:227], v150, s[40:41]
	global_load_dwordx4 v[228:231], v150, s[40:41] offset:512
	v_lshlrev_b32_e32 v148, 12, v148
	v_lshl_add_u32 v149, v149, 2, v148
	v_lshl_add_u32 v144, v147, 4, v149
	s_mov_b32 s38, 0x01010101
	s_mov_b32 s39, 0x01010101
	v_mov_b32_e32 v145, v144
	v_add_u32_e32 v146, 0x8000, v144
	global_load_dwordx4 v[192:195], v145, s[72:73]
	global_load_dwordx4 v[196:199], v146, s[72:73]
	v_add_u32_e32 v147, 0x200, v144
	v_add_u32_e32 v148, 0x8200, v144
	global_load_dwordx4 v[200:203], v147, s[72:73]
	global_load_dwordx4 v[204:207], v148, s[72:73]
	ds_write_b128 v152, v[126:129]
	ds_write_b128 v152, v[122:125] offset:16
	ds_read_b128 v[240:243], v153
	ds_read_b128 v[244:247], v153 offset:1152
	ds_write_b128 v152, v[118:121]
	ds_write_b128 v152, v[114:117] offset:16
	ds_read_b128 v[130:133], v153
	ds_read_b128 v[176:179], v153 offset:1152
	s_waitcnt lgkmcnt(4)
	s_waitcnt vmcnt(2)
	v_pk_add_f32 v[240:241], v[240:241], v[192:193]
	v_pk_add_f32 v[242:243], v[242:243], v[194:195]
	v_pk_add_f32 v[244:245], v[244:245], v[196:197]
	v_pk_add_f32 v[246:247], v[246:247], v[198:199]
	v_mov_b32_e32 v180, v144
	v_add_u32_e32 v181, 0x8000, v144
	global_store_dwordx4 v180, v[240:243], s[72:73]
	global_store_dwordx4 v181, v[244:247], s[72:73]
	v_mul_f32_e32 v232, v240, v240
	v_fmac_f32_e32 v232, v241, v241
	v_fmac_f32_e32 v232, v242, v242
	v_fmac_f32_e32 v232, v243, v243
	v_mul_f32_e32 v233, v244, v244
	v_fmac_f32_e32 v233, v245, v245
	v_fmac_f32_e32 v233, v246, v246
	v_fmac_f32_e32 v233, v247, v247
	v_pk_mul_f32 v[248:249], v[240:241], v[224:225]
	v_pk_mul_f32 v[242:243], v[242:243], v[226:227]
	v_cvt_pk_bf16_f32 v216, v248, v249
	v_cvt_pk_bf16_f32 v217, v242, v243
	v_pk_mul_f32 v[248:249], v[244:245], v[224:225]
	v_pk_mul_f32 v[246:247], v[246:247], v[226:227]
	v_cvt_pk_bf16_f32 v218, v248, v249
	v_cvt_pk_bf16_f32 v219, v246, v247
	v_add_u32_e32 v145, 0x10000, v144
	v_add_u32_e32 v146, 0x18000, v144
	global_load_dwordx4 v[192:195], v145, s[72:73]
	global_load_dwordx4 v[196:199], v146, s[72:73]
	v_add_u32_e32 v147, 0x10200, v144
	v_add_u32_e32 v148, 0x18200, v144
	global_load_dwordx4 v[126:129], v147, s[72:73]
	global_load_dwordx4 v[122:125], v148, s[72:73]
	ds_write_b128 v152, v[108:111]
	ds_write_b128 v152, v[104:107] offset:16
	ds_read_b128 v[240:243], v153
	ds_read_b128 v[244:247], v153 offset:1152
	s_waitcnt lgkmcnt(4)
	s_waitcnt vmcnt(6)
	v_pk_add_f32 v[130:131], v[130:131], v[200:201]
	v_pk_add_f32 v[132:133], v[132:133], v[202:203]
	v_pk_add_f32 v[176:177], v[176:177], v[204:205]
	v_pk_add_f32 v[178:179], v[178:179], v[206:207]
	v_add_u32_e32 v180, 0x200, v144
	v_add_u32_e32 v181, 0x8200, v144
	global_store_dwordx4 v180, v[130:133], s[72:73]
	global_store_dwordx4 v181, v[176:179], s[72:73]
	v_fmac_f32_e32 v232, v130, v130
	v_fmac_f32_e32 v232, v131, v131
	v_fmac_f32_e32 v232, v132, v132
	v_fmac_f32_e32 v232, v133, v133
	v_fmac_f32_e32 v233, v176, v176
	v_fmac_f32_e32 v233, v177, v177
	v_fmac_f32_e32 v233, v178, v178
	v_fmac_f32_e32 v233, v179, v179
	v_pk_mul_f32 v[248:249], v[130:131], v[228:229]
	v_pk_mul_f32 v[132:133], v[132:133], v[230:231]
	v_cvt_pk_bf16_f32 v220, v248, v249
	v_cvt_pk_bf16_f32 v221, v132, v133
	v_pk_mul_f32 v[248:249], v[176:177], v[228:229]
	v_pk_mul_f32 v[178:179], v[178:179], v[230:231]
	v_cvt_pk_bf16_f32 v222, v248, v249
	v_cvt_pk_bf16_f32 v223, v178, v179
	ds_write_b64 v234, v[216:217]
	ds_write_b64 v234, v[220:221] offset:64
	ds_write_b64 v234, v[218:219] offset:1152
	ds_write_b64 v234, v[222:223] offset:1216
	ds_read_b128 v[208:211], v153
	ds_read_b128 v[212:215], v153 offset:1152
	s_nop 0
	v_add_f32_dpp v232, v232, v232 quad_perm:[1,0,3,2] row_mask:0xf bank_mask:0xf
	v_add_f32_dpp v233, v233, v233 quad_perm:[1,0,3,2] row_mask:0xf bank_mask:0xf
	s_nop 0
	v_add_f32_dpp v232, v232, v232 quad_perm:[2,3,0,1] row_mask:0xf bank_mask:0xf
	v_add_f32_dpp v233, v233, v233 quad_perm:[2,3,0,1] row_mask:0xf bank_mask:0xf
	s_nop 0
	v_add_f32_dpp v232, v232, v232 row_half_mirror row_mask:0xf bank_mask:0xf
	v_add_f32_dpp v233, v233, v233 row_half_mirror row_mask:0xf bank_mask:0xf
	s_nop 0
	v_cndmask_b32_e64 v149, v149, v232, s[38:39]
	v_cndmask_b32_e64 v150, v150, v233, s[38:39]
	v_add_u32_e32 v145, 0x20000, v144
	v_add_u32_e32 v146, 0x28000, v144
	global_load_dwordx4 v[200:203], v145, s[72:73]
	global_load_dwordx4 v[204:207], v146, s[72:73]
	v_add_u32_e32 v147, 0x20200, v144
	v_add_u32_e32 v148, 0x28200, v144
	global_load_dwordx4 v[118:121], v147, s[72:73]
	global_load_dwordx4 v[114:117], v148, s[72:73]
	ds_write_b128 v152, v[100:103]
	ds_write_b128 v152, v[96:99] offset:16
	ds_read_b128 v[130:133], v153
	ds_read_b128 v[176:179], v153 offset:1152
	s_waitcnt lgkmcnt(4)
	s_waitcnt vmcnt(8)
	v_mov_b32_e32 v170, v239
	v_add_u32_e32 v171, 0x4000, v239
	global_store_dwordx4 v170, v[208:211], s[68:69]
	global_store_dwordx4 v171, v[212:215], s[68:69]
	v_pk_add_f32 v[240:241], v[240:241], v[192:193]
	v_pk_add_f32 v[242:243], v[242:243], v[194:195]
	v_pk_add_f32 v[244:245], v[244:245], v[196:197]
	v_pk_add_f32 v[246:247], v[246:247], v[198:199]
	v_add_u32_e32 v180, 0x10000, v144
	v_add_u32_e32 v181, 0x18000, v144
	global_store_dwordx4 v180, v[240:243], s[72:73]
	global_store_dwordx4 v181, v[244:247], s[72:73]
	v_mul_f32_e32 v232, v240, v240
	v_fmac_f32_e32 v232, v241, v241
	v_fmac_f32_e32 v232, v242, v242
	v_fmac_f32_e32 v232, v243, v243
	v_mul_f32_e32 v233, v244, v244
	v_fmac_f32_e32 v233, v245, v245
	v_fmac_f32_e32 v233, v246, v246
	v_fmac_f32_e32 v233, v247, v247
	v_pk_mul_f32 v[248:249], v[240:241], v[224:225]
	v_pk_mul_f32 v[242:243], v[242:243], v[226:227]
	v_cvt_pk_bf16_f32 v216, v248, v249
	v_cvt_pk_bf16_f32 v217, v242, v243
	v_pk_mul_f32 v[248:249], v[244:245], v[224:225]
	v_pk_mul_f32 v[246:247], v[246:247], v[226:227]
	v_cvt_pk_bf16_f32 v218, v248, v249
	v_cvt_pk_bf16_f32 v219, v246, v247
	v_add_u32_e32 v145, 0x30000, v144
	v_add_u32_e32 v146, 0x38000, v144
	global_load_dwordx4 v[192:195], v145, s[72:73]
	global_load_dwordx4 v[196:199], v146, s[72:73]
	v_add_u32_e32 v147, 0x30200, v144
	v_add_u32_e32 v148, 0x38200, v144
	global_load_dwordx4 v[108:111], v147, s[72:73]
	global_load_dwordx4 v[104:107], v148, s[72:73]
	ds_write_b128 v152, v[92:95]
	ds_write_b128 v152, v[88:91] offset:16
	ds_read_b128 v[240:243], v153
	ds_read_b128 v[244:247], v153 offset:1152
	s_waitcnt lgkmcnt(4)
	s_waitcnt vmcnt(14)
	v_pk_add_f32 v[130:131], v[130:131], v[126:127]
	v_pk_add_f32 v[132:133], v[132:133], v[128:129]
	v_pk_add_f32 v[176:177], v[176:177], v[122:123]
	v_pk_add_f32 v[178:179], v[178:179], v[124:125]
	v_add_u32_e32 v180, 0x10200, v144
	v_add_u32_e32 v181, 0x18200, v144
	global_store_dwordx4 v180, v[130:133], s[72:73]
	global_store_dwordx4 v181, v[176:179], s[72:73]
	v_fmac_f32_e32 v232, v130, v130
	v_fmac_f32_e32 v232, v131, v131
	v_fmac_f32_e32 v232, v132, v132
	v_fmac_f32_e32 v232, v133, v133
	v_fmac_f32_e32 v233, v176, v176
	v_fmac_f32_e32 v233, v177, v177
	v_fmac_f32_e32 v233, v178, v178
	v_fmac_f32_e32 v233, v179, v179
	v_pk_mul_f32 v[248:249], v[130:131], v[228:229]
	v_pk_mul_f32 v[132:133], v[132:133], v[230:231]
	v_cvt_pk_bf16_f32 v220, v248, v249
	v_cvt_pk_bf16_f32 v221, v132, v133
	v_pk_mul_f32 v[248:249], v[176:177], v[228:229]
	v_pk_mul_f32 v[178:179], v[178:179], v[230:231]
	v_cvt_pk_bf16_f32 v222, v248, v249
	v_cvt_pk_bf16_f32 v223, v178, v179
	ds_write_b64 v234, v[216:217]
	ds_write_b64 v234, v[220:221] offset:64
	ds_write_b64 v234, v[218:219] offset:1152
	ds_write_b64 v234, v[222:223] offset:1216
	ds_read_b128 v[208:211], v153
	ds_read_b128 v[212:215], v153 offset:1152
	s_nop 0
	v_add_f32_dpp v232, v232, v232 quad_perm:[1,0,3,2] row_mask:0xf bank_mask:0xf
	v_add_f32_dpp v233, v233, v233 quad_perm:[1,0,3,2] row_mask:0xf bank_mask:0xf
	s_nop 0
	v_add_f32_dpp v232, v232, v232 quad_perm:[2,3,0,1] row_mask:0xf bank_mask:0xf
	v_add_f32_dpp v233, v233, v233 quad_perm:[2,3,0,1] row_mask:0xf bank_mask:0xf
	s_nop 0
	v_add_f32_dpp v232, v232, v232 row_half_mirror row_mask:0xf bank_mask:0xf
	v_add_f32_dpp v233, v233, v233 row_half_mirror row_mask:0xf bank_mask:0xf
	s_nop 0
	s_lshl_b64 s[18:19], s[38:39], 1
	v_cndmask_b32_e64 v149, v149, v232, s[18:19]
	v_cndmask_b32_e64 v150, v150, v233, s[18:19]
	v_add_u32_e32 v145, 0x80000, v144
	v_add_u32_e32 v146, 0x88000, v144
	global_load_dwordx4 v[126:129], v145, s[72:73]
	global_load_dwordx4 v[122:125], v146, s[72:73]
	v_add_u32_e32 v147, 0x80200, v144
	v_add_u32_e32 v148, 0x88200, v144
	global_load_dwordx4 v[100:103], v147, s[72:73]
	global_load_dwordx4 v[96:99], v148, s[72:73]
	ds_write_b128 v152, v[84:87]
	ds_write_b128 v152, v[80:83] offset:16
	ds_read_b128 v[130:133], v153
	ds_read_b128 v[176:179], v153 offset:1152
	s_waitcnt lgkmcnt(4)
	s_waitcnt vmcnt(16)
	v_add_u32_e32 v170, 0x8000, v239
	v_add_u32_e32 v171, 0xc000, v239
	global_store_dwordx4 v170, v[208:211], s[68:69]
	global_store_dwordx4 v171, v[212:215], s[68:69]
	v_pk_add_f32 v[240:241], v[240:241], v[200:201]
	v_pk_add_f32 v[242:243], v[242:243], v[202:203]
	v_pk_add_f32 v[244:245], v[244:245], v[204:205]
	v_pk_add_f32 v[246:247], v[246:247], v[206:207]
	v_add_u32_e32 v180, 0x20000, v144
	v_add_u32_e32 v181, 0x28000, v144
	global_store_dwordx4 v180, v[240:243], s[72:73]
	global_store_dwordx4 v181, v[244:247], s[72:73]
	v_mul_f32_e32 v232, v240, v240
	v_fmac_f32_e32 v232, v241, v241
	v_fmac_f32_e32 v232, v242, v242
	v_fmac_f32_e32 v232, v243, v243
	v_mul_f32_e32 v233, v244, v244
	v_fmac_f32_e32 v233, v245, v245
	v_fmac_f32_e32 v233, v246, v246
	v_fmac_f32_e32 v233, v247, v247
	v_pk_mul_f32 v[248:249], v[240:241], v[224:225]
	v_pk_mul_f32 v[242:243], v[242:243], v[226:227]
	v_cvt_pk_bf16_f32 v216, v248, v249
	v_cvt_pk_bf16_f32 v217, v242, v243
	v_pk_mul_f32 v[248:249], v[244:245], v[224:225]
	v_pk_mul_f32 v[246:247], v[246:247], v[226:227]
	v_cvt_pk_bf16_f32 v218, v248, v249
	v_cvt_pk_bf16_f32 v219, v246, v247
	v_add_u32_e32 v145, 0x90000, v144
	v_add_u32_e32 v146, 0x98000, v144
	global_load_dwordx4 v[200:203], v145, s[72:73]
	global_load_dwordx4 v[204:207], v146, s[72:73]
	v_add_u32_e32 v147, 0x90200, v144
	v_add_u32_e32 v148, 0x98200, v144
	global_load_dwordx4 v[92:95], v147, s[72:73]
	global_load_dwordx4 v[88:91], v148, s[72:73]
	ds_write_b128 v152, v[76:79]
	ds_write_b128 v152, v[72:75] offset:16
	ds_read_b128 v[240:243], v153
	ds_read_b128 v[244:247], v153 offset:1152
	s_waitcnt lgkmcnt(4)
	s_waitcnt vmcnt(22)
	v_pk_add_f32 v[130:131], v[130:131], v[118:119]
	v_pk_add_f32 v[132:133], v[132:133], v[120:121]
	v_pk_add_f32 v[176:177], v[176:177], v[114:115]
	v_pk_add_f32 v[178:179], v[178:179], v[116:117]
	v_add_u32_e32 v180, 0x20200, v144
	v_add_u32_e32 v181, 0x28200, v144
	global_store_dwordx4 v180, v[130:133], s[72:73]
	global_store_dwordx4 v181, v[176:179], s[72:73]
	v_fmac_f32_e32 v232, v130, v130
	v_fmac_f32_e32 v232, v131, v131
	v_fmac_f32_e32 v232, v132, v132
	v_fmac_f32_e32 v232, v133, v133
	v_fmac_f32_e32 v233, v176, v176
	v_fmac_f32_e32 v233, v177, v177
	v_fmac_f32_e32 v233, v178, v178
	v_fmac_f32_e32 v233, v179, v179
	v_pk_mul_f32 v[248:249], v[130:131], v[228:229]
	v_pk_mul_f32 v[132:133], v[132:133], v[230:231]
	v_cvt_pk_bf16_f32 v220, v248, v249
	v_cvt_pk_bf16_f32 v221, v132, v133
	v_pk_mul_f32 v[248:249], v[176:177], v[228:229]
	v_pk_mul_f32 v[178:179], v[178:179], v[230:231]
	v_cvt_pk_bf16_f32 v222, v248, v249
	v_cvt_pk_bf16_f32 v223, v178, v179
	ds_write_b64 v234, v[216:217]
	ds_write_b64 v234, v[220:221] offset:64
	ds_write_b64 v234, v[218:219] offset:1152
	ds_write_b64 v234, v[222:223] offset:1216
	ds_read_b128 v[208:211], v153
	ds_read_b128 v[212:215], v153 offset:1152
	s_nop 0
	v_add_f32_dpp v232, v232, v232 quad_perm:[1,0,3,2] row_mask:0xf bank_mask:0xf
	v_add_f32_dpp v233, v233, v233 quad_perm:[1,0,3,2] row_mask:0xf bank_mask:0xf
	s_nop 0
	v_add_f32_dpp v232, v232, v232 quad_perm:[2,3,0,1] row_mask:0xf bank_mask:0xf
	v_add_f32_dpp v233, v233, v233 quad_perm:[2,3,0,1] row_mask:0xf bank_mask:0xf
	s_nop 0
	v_add_f32_dpp v232, v232, v232 row_half_mirror row_mask:0xf bank_mask:0xf
	v_add_f32_dpp v233, v233, v233 row_half_mirror row_mask:0xf bank_mask:0xf
	s_nop 0
	s_lshl_b64 s[18:19], s[38:39], 2
	v_cndmask_b32_e64 v149, v149, v232, s[18:19]
	v_cndmask_b32_e64 v150, v150, v233, s[18:19]
	v_add_u32_e32 v145, 0xa0000, v144
	v_add_u32_e32 v146, 0xa8000, v144
	global_load_dwordx4 v[118:121], v145, s[72:73]
	global_load_dwordx4 v[114:117], v146, s[72:73]
	v_add_u32_e32 v147, 0xa0200, v144
	v_add_u32_e32 v148, 0xa8200, v144
	global_load_dwordx4 v[84:87], v147, s[72:73]
	global_load_dwordx4 v[80:83], v148, s[72:73]
	ds_write_b128 v152, v[68:71]
	ds_write_b128 v152, v[64:67] offset:16
	ds_read_b128 v[130:133], v153
	ds_read_b128 v[176:179], v153 offset:1152
	s_waitcnt lgkmcnt(4)
	s_waitcnt vmcnt(22)
	v_add_u32_e32 v170, 0x10000, v239
	v_add_u32_e32 v171, 0x14000, v239
	global_store_dwordx4 v170, v[208:211], s[68:69]
	global_store_dwordx4 v171, v[212:215], s[68:69]
	v_pk_add_f32 v[240:241], v[240:241], v[192:193]
	v_pk_add_f32 v[242:243], v[242:243], v[194:195]
	v_pk_add_f32 v[244:245], v[244:245], v[196:197]
	v_pk_add_f32 v[246:247], v[246:247], v[198:199]
	v_add_u32_e32 v180, 0x30000, v144
	v_add_u32_e32 v181, 0x38000, v144
	global_store_dwordx4 v180, v[240:243], s[72:73]
	global_store_dwordx4 v181, v[244:247], s[72:73]
	v_mul_f32_e32 v232, v240, v240
	v_fmac_f32_e32 v232, v241, v241
	v_fmac_f32_e32 v232, v242, v242
	v_fmac_f32_e32 v232, v243, v243
	v_mul_f32_e32 v233, v244, v244
	v_fmac_f32_e32 v233, v245, v245
	v_fmac_f32_e32 v233, v246, v246
	v_fmac_f32_e32 v233, v247, v247
	v_pk_mul_f32 v[248:249], v[240:241], v[224:225]
	v_pk_mul_f32 v[242:243], v[242:243], v[226:227]
	v_cvt_pk_bf16_f32 v216, v248, v249
	v_cvt_pk_bf16_f32 v217, v242, v243
	v_pk_mul_f32 v[248:249], v[244:245], v[224:225]
	v_pk_mul_f32 v[246:247], v[246:247], v[226:227]
	v_cvt_pk_bf16_f32 v218, v248, v249
	v_cvt_pk_bf16_f32 v219, v246, v247
	v_add_u32_e32 v145, 0xb0000, v144
	v_add_u32_e32 v146, 0xb8000, v144
	global_load_dwordx4 v[192:195], v145, s[72:73]
	global_load_dwordx4 v[196:199], v146, s[72:73]
	v_add_u32_e32 v147, 0xb0200, v144
	v_add_u32_e32 v148, 0xb8200, v144
	global_load_dwordx4 v[76:79], v147, s[72:73]
	global_load_dwordx4 v[72:75], v148, s[72:73]
	ds_write_b128 v152, v[60:63]
	ds_write_b128 v152, v[56:59] offset:16
	ds_read_b128 v[240:243], v153
	ds_read_b128 v[244:247], v153 offset:1152
	s_waitcnt lgkmcnt(4)
	s_waitcnt vmcnt(28)
	v_pk_add_f32 v[130:131], v[130:131], v[108:109]
	v_pk_add_f32 v[132:133], v[132:133], v[110:111]
	v_pk_add_f32 v[176:177], v[176:177], v[104:105]
	v_pk_add_f32 v[178:179], v[178:179], v[106:107]
	v_add_u32_e32 v180, 0x30200, v144
	v_add_u32_e32 v181, 0x38200, v144
	global_store_dwordx4 v180, v[130:133], s[72:73]
	global_store_dwordx4 v181, v[176:179], s[72:73]
	v_fmac_f32_e32 v232, v130, v130
	v_fmac_f32_e32 v232, v131, v131
	v_fmac_f32_e32 v232, v132, v132
	v_fmac_f32_e32 v232, v133, v133
	v_fmac_f32_e32 v233, v176, v176
	v_fmac_f32_e32 v233, v177, v177
	v_fmac_f32_e32 v233, v178, v178
	v_fmac_f32_e32 v233, v179, v179
	v_pk_mul_f32 v[248:249], v[130:131], v[228:229]
	v_pk_mul_f32 v[132:133], v[132:133], v[230:231]
	v_cvt_pk_bf16_f32 v220, v248, v249
	v_cvt_pk_bf16_f32 v221, v132, v133
	v_pk_mul_f32 v[248:249], v[176:177], v[228:229]
	v_pk_mul_f32 v[178:179], v[178:179], v[230:231]
	v_cvt_pk_bf16_f32 v222, v248, v249
	v_cvt_pk_bf16_f32 v223, v178, v179
	ds_write_b64 v234, v[216:217]
	ds_write_b64 v234, v[220:221] offset:64
	ds_write_b64 v234, v[218:219] offset:1152
	ds_write_b64 v234, v[222:223] offset:1216
	ds_read_b128 v[208:211], v153
	ds_read_b128 v[212:215], v153 offset:1152
	s_nop 0
	v_add_f32_dpp v232, v232, v232 quad_perm:[1,0,3,2] row_mask:0xf bank_mask:0xf
	v_add_f32_dpp v233, v233, v233 quad_perm:[1,0,3,2] row_mask:0xf bank_mask:0xf
	s_nop 0
	v_add_f32_dpp v232, v232, v232 quad_perm:[2,3,0,1] row_mask:0xf bank_mask:0xf
	v_add_f32_dpp v233, v233, v233 quad_perm:[2,3,0,1] row_mask:0xf bank_mask:0xf
	s_nop 0
	v_add_f32_dpp v232, v232, v232 row_half_mirror row_mask:0xf bank_mask:0xf
	v_add_f32_dpp v233, v233, v233 row_half_mirror row_mask:0xf bank_mask:0xf
	s_nop 0
	s_lshl_b64 s[18:19], s[38:39], 3
	v_cndmask_b32_e64 v149, v149, v232, s[18:19]
	v_cndmask_b32_e64 v150, v150, v233, s[18:19]
	ds_write_b128 v152, v[52:55]
	ds_write_b128 v152, v[48:51] offset:16
	ds_read_b128 v[130:133], v153
	ds_read_b128 v[176:179], v153 offset:1152
	s_waitcnt lgkmcnt(4)
	s_waitcnt vmcnt(26)
	v_add_u32_e32 v170, 0x18000, v239
	v_add_u32_e32 v171, 0x1c000, v239
	global_store_dwordx4 v170, v[208:211], s[68:69]
	global_store_dwordx4 v171, v[212:215], s[68:69]
	v_pk_add_f32 v[240:241], v[240:241], v[126:127]
	v_pk_add_f32 v[242:243], v[242:243], v[128:129]
	v_pk_add_f32 v[244:245], v[244:245], v[122:123]
	v_pk_add_f32 v[246:247], v[246:247], v[124:125]
	v_add_u32_e32 v180, 0x80000, v144
	v_add_u32_e32 v181, 0x88000, v144
	global_store_dwordx4 v180, v[240:243], s[72:73]
	global_store_dwordx4 v181, v[244:247], s[72:73]
	v_mul_f32_e32 v232, v240, v240
	v_fmac_f32_e32 v232, v241, v241
	v_fmac_f32_e32 v232, v242, v242
	v_fmac_f32_e32 v232, v243, v243
	v_mul_f32_e32 v233, v244, v244
	v_fmac_f32_e32 v233, v245, v245
	v_fmac_f32_e32 v233, v246, v246
	v_fmac_f32_e32 v233, v247, v247
	v_pk_mul_f32 v[248:249], v[240:241], v[224:225]
	v_pk_mul_f32 v[242:243], v[242:243], v[226:227]
	v_cvt_pk_bf16_f32 v216, v248, v249
	v_cvt_pk_bf16_f32 v217, v242, v243
	v_pk_mul_f32 v[248:249], v[244:245], v[224:225]
	v_pk_mul_f32 v[246:247], v[246:247], v[226:227]
	v_cvt_pk_bf16_f32 v218, v248, v249
	v_cvt_pk_bf16_f32 v219, v246, v247
	ds_write_b128 v152, v[44:47]
	ds_write_b128 v152, v[40:43] offset:16
	ds_read_b128 v[240:243], v153
	ds_read_b128 v[244:247], v153 offset:1152
	s_waitcnt lgkmcnt(4)
	s_waitcnt vmcnt(28)
	v_pk_add_f32 v[130:131], v[130:131], v[100:101]
	v_pk_add_f32 v[132:133], v[132:133], v[102:103]
	v_pk_add_f32 v[176:177], v[176:177], v[96:97]
	v_pk_add_f32 v[178:179], v[178:179], v[98:99]
	v_add_u32_e32 v180, 0x80200, v144
	v_add_u32_e32 v181, 0x88200, v144
	global_store_dwordx4 v180, v[130:133], s[72:73]
	global_store_dwordx4 v181, v[176:179], s[72:73]
	v_fmac_f32_e32 v232, v130, v130
	v_fmac_f32_e32 v232, v131, v131
	v_fmac_f32_e32 v232, v132, v132
	v_fmac_f32_e32 v232, v133, v133
	v_fmac_f32_e32 v233, v176, v176
	v_fmac_f32_e32 v233, v177, v177
	v_fmac_f32_e32 v233, v178, v178
	v_fmac_f32_e32 v233, v179, v179
	v_pk_mul_f32 v[248:249], v[130:131], v[228:229]
	v_pk_mul_f32 v[132:133], v[132:133], v[230:231]
	v_cvt_pk_bf16_f32 v220, v248, v249
	v_cvt_pk_bf16_f32 v221, v132, v133
	v_pk_mul_f32 v[248:249], v[176:177], v[228:229]
	v_pk_mul_f32 v[178:179], v[178:179], v[230:231]
	v_cvt_pk_bf16_f32 v222, v248, v249
	v_cvt_pk_bf16_f32 v223, v178, v179
	ds_write_b64 v234, v[216:217]
	ds_write_b64 v234, v[220:221] offset:64
	ds_write_b64 v234, v[218:219] offset:1152
	ds_write_b64 v234, v[222:223] offset:1216
	ds_read_b128 v[208:211], v153
	ds_read_b128 v[212:215], v153 offset:1152
	s_nop 0
	v_add_f32_dpp v232, v232, v232 quad_perm:[1,0,3,2] row_mask:0xf bank_mask:0xf
	v_add_f32_dpp v233, v233, v233 quad_perm:[1,0,3,2] row_mask:0xf bank_mask:0xf
	s_nop 0
	v_add_f32_dpp v232, v232, v232 quad_perm:[2,3,0,1] row_mask:0xf bank_mask:0xf
	v_add_f32_dpp v233, v233, v233 quad_perm:[2,3,0,1] row_mask:0xf bank_mask:0xf
	s_nop 0
	v_add_f32_dpp v232, v232, v232 row_half_mirror row_mask:0xf bank_mask:0xf
	v_add_f32_dpp v233, v233, v233 row_half_mirror row_mask:0xf bank_mask:0xf
	s_nop 0
	s_lshl_b64 s[18:19], s[38:39], 4
	v_cndmask_b32_e64 v149, v149, v232, s[18:19]
	v_cndmask_b32_e64 v150, v150, v233, s[18:19]
	ds_write_b128 v152, v[36:39]
	ds_write_b128 v152, v[32:35] offset:16
	ds_read_b128 v[130:133], v153
	ds_read_b128 v[176:179], v153 offset:1152
	s_waitcnt lgkmcnt(4)
	s_waitcnt vmcnt(24)
	v_add_u32_e32 v170, 0x40000, v239
	v_add_u32_e32 v171, 0x44000, v239
	global_store_dwordx4 v170, v[208:211], s[68:69]
	global_store_dwordx4 v171, v[212:215], s[68:69]
	v_pk_add_f32 v[240:241], v[240:241], v[200:201]
	v_pk_add_f32 v[242:243], v[242:243], v[202:203]
	v_pk_add_f32 v[244:245], v[244:245], v[204:205]
	v_pk_add_f32 v[246:247], v[246:247], v[206:207]
	v_add_u32_e32 v180, 0x90000, v144
	v_add_u32_e32 v181, 0x98000, v144
	global_store_dwordx4 v180, v[240:243], s[72:73]
	global_store_dwordx4 v181, v[244:247], s[72:73]
	v_mul_f32_e32 v232, v240, v240
	v_fmac_f32_e32 v232, v241, v241
	v_fmac_f32_e32 v232, v242, v242
	v_fmac_f32_e32 v232, v243, v243
	v_mul_f32_e32 v233, v244, v244
	v_fmac_f32_e32 v233, v245, v245
	v_fmac_f32_e32 v233, v246, v246
	v_fmac_f32_e32 v233, v247, v247
	v_pk_mul_f32 v[248:249], v[240:241], v[224:225]
	v_pk_mul_f32 v[242:243], v[242:243], v[226:227]
	v_cvt_pk_bf16_f32 v216, v248, v249
	v_cvt_pk_bf16_f32 v217, v242, v243
	v_pk_mul_f32 v[248:249], v[244:245], v[224:225]
	v_pk_mul_f32 v[246:247], v[246:247], v[226:227]
	v_cvt_pk_bf16_f32 v218, v248, v249
	v_cvt_pk_bf16_f32 v219, v246, v247
	ds_write_b128 v152, v[28:31]
	ds_write_b128 v152, v[24:27] offset:16
	ds_read_b128 v[240:243], v153
	ds_read_b128 v[244:247], v153 offset:1152
	s_waitcnt lgkmcnt(4)
	s_waitcnt vmcnt(26)
	v_pk_add_f32 v[130:131], v[130:131], v[92:93]
	v_pk_add_f32 v[132:133], v[132:133], v[94:95]
	v_pk_add_f32 v[176:177], v[176:177], v[88:89]
	v_pk_add_f32 v[178:179], v[178:179], v[90:91]
	v_add_u32_e32 v180, 0x90200, v144
	v_add_u32_e32 v181, 0x98200, v144
	global_store_dwordx4 v180, v[130:133], s[72:73]
	global_store_dwordx4 v181, v[176:179], s[72:73]
	v_fmac_f32_e32 v232, v130, v130
	v_fmac_f32_e32 v232, v131, v131
	v_fmac_f32_e32 v232, v132, v132
	v_fmac_f32_e32 v232, v133, v133
	v_fmac_f32_e32 v233, v176, v176
	v_fmac_f32_e32 v233, v177, v177
	v_fmac_f32_e32 v233, v178, v178
	v_fmac_f32_e32 v233, v179, v179
	v_pk_mul_f32 v[248:249], v[130:131], v[228:229]
	v_pk_mul_f32 v[132:133], v[132:133], v[230:231]
	v_cvt_pk_bf16_f32 v220, v248, v249
	v_cvt_pk_bf16_f32 v221, v132, v133
	v_pk_mul_f32 v[248:249], v[176:177], v[228:229]
	v_pk_mul_f32 v[178:179], v[178:179], v[230:231]
	v_cvt_pk_bf16_f32 v222, v248, v249
	v_cvt_pk_bf16_f32 v223, v178, v179
	ds_write_b64 v234, v[216:217]
	ds_write_b64 v234, v[220:221] offset:64
	ds_write_b64 v234, v[218:219] offset:1152
	ds_write_b64 v234, v[222:223] offset:1216
	ds_read_b128 v[208:211], v153
	ds_read_b128 v[212:215], v153 offset:1152
	s_nop 0
	v_add_f32_dpp v232, v232, v232 quad_perm:[1,0,3,2] row_mask:0xf bank_mask:0xf
	v_add_f32_dpp v233, v233, v233 quad_perm:[1,0,3,2] row_mask:0xf bank_mask:0xf
	s_nop 0
	v_add_f32_dpp v232, v232, v232 quad_perm:[2,3,0,1] row_mask:0xf bank_mask:0xf
	v_add_f32_dpp v233, v233, v233 quad_perm:[2,3,0,1] row_mask:0xf bank_mask:0xf
	s_nop 0
	v_add_f32_dpp v232, v232, v232 row_half_mirror row_mask:0xf bank_mask:0xf
	v_add_f32_dpp v233, v233, v233 row_half_mirror row_mask:0xf bank_mask:0xf
	s_nop 0
	s_lshl_b64 s[18:19], s[38:39], 5
	v_cndmask_b32_e64 v149, v149, v232, s[18:19]
	v_cndmask_b32_e64 v150, v150, v233, s[18:19]
	ds_write_b128 v152, v[20:23]
	ds_write_b128 v152, v[16:19] offset:16
	ds_read_b128 v[130:133], v153
	ds_read_b128 v[176:179], v153 offset:1152
	s_waitcnt lgkmcnt(4)
	s_waitcnt vmcnt(24)
	v_add_u32_e32 v170, 0x48000, v239
	v_add_u32_e32 v171, 0x4c000, v239
	global_store_dwordx4 v170, v[208:211], s[68:69]
	global_store_dwordx4 v171, v[212:215], s[68:69]
	v_pk_add_f32 v[240:241], v[240:241], v[118:119]
	v_pk_add_f32 v[242:243], v[242:243], v[120:121]
	v_pk_add_f32 v[244:245], v[244:245], v[114:115]
	v_pk_add_f32 v[246:247], v[246:247], v[116:117]
	v_add_u32_e32 v180, 0xa0000, v144
	v_add_u32_e32 v181, 0xa8000, v144
	global_store_dwordx4 v180, v[240:243], s[72:73]
	global_store_dwordx4 v181, v[244:247], s[72:73]
	v_mul_f32_e32 v232, v240, v240
	v_fmac_f32_e32 v232, v241, v241
	v_fmac_f32_e32 v232, v242, v242
	v_fmac_f32_e32 v232, v243, v243
	v_mul_f32_e32 v233, v244, v244
	v_fmac_f32_e32 v233, v245, v245
	v_fmac_f32_e32 v233, v246, v246
	v_fmac_f32_e32 v233, v247, v247
	v_pk_mul_f32 v[248:249], v[240:241], v[224:225]
	v_pk_mul_f32 v[242:243], v[242:243], v[226:227]
	v_cvt_pk_bf16_f32 v216, v248, v249
	v_cvt_pk_bf16_f32 v217, v242, v243
	v_pk_mul_f32 v[248:249], v[244:245], v[224:225]
	v_pk_mul_f32 v[246:247], v[246:247], v[226:227]
	v_cvt_pk_bf16_f32 v218, v248, v249
	v_cvt_pk_bf16_f32 v219, v246, v247
	ds_write_b128 v152, v[12:15]
	ds_write_b128 v152, v[8:11] offset:16
	ds_read_b128 v[240:243], v153
	ds_read_b128 v[244:247], v153 offset:1152
	s_waitcnt lgkmcnt(4)
	s_waitcnt vmcnt(26)
	v_pk_add_f32 v[130:131], v[130:131], v[84:85]
	v_pk_add_f32 v[132:133], v[132:133], v[86:87]
	v_pk_add_f32 v[176:177], v[176:177], v[80:81]
	v_pk_add_f32 v[178:179], v[178:179], v[82:83]
	v_add_u32_e32 v180, 0xa0200, v144
	v_add_u32_e32 v181, 0xa8200, v144
	global_store_dwordx4 v180, v[130:133], s[72:73]
	global_store_dwordx4 v181, v[176:179], s[72:73]
	v_fmac_f32_e32 v232, v130, v130
	v_fmac_f32_e32 v232, v131, v131
	v_fmac_f32_e32 v232, v132, v132
	v_fmac_f32_e32 v232, v133, v133
	v_fmac_f32_e32 v233, v176, v176
	v_fmac_f32_e32 v233, v177, v177
	v_fmac_f32_e32 v233, v178, v178
	v_fmac_f32_e32 v233, v179, v179
	v_pk_mul_f32 v[248:249], v[130:131], v[228:229]
	v_pk_mul_f32 v[132:133], v[132:133], v[230:231]
	v_cvt_pk_bf16_f32 v220, v248, v249
	v_cvt_pk_bf16_f32 v221, v132, v133
	v_pk_mul_f32 v[248:249], v[176:177], v[228:229]
	v_pk_mul_f32 v[178:179], v[178:179], v[230:231]
	v_cvt_pk_bf16_f32 v222, v248, v249
	v_cvt_pk_bf16_f32 v223, v178, v179
	ds_write_b64 v234, v[216:217]
	ds_write_b64 v234, v[220:221] offset:64
	ds_write_b64 v234, v[218:219] offset:1152
	ds_write_b64 v234, v[222:223] offset:1216
	ds_read_b128 v[208:211], v153
	ds_read_b128 v[212:215], v153 offset:1152
	s_nop 0
	v_add_f32_dpp v232, v232, v232 quad_perm:[1,0,3,2] row_mask:0xf bank_mask:0xf
	v_add_f32_dpp v233, v233, v233 quad_perm:[1,0,3,2] row_mask:0xf bank_mask:0xf
	s_nop 0
	v_add_f32_dpp v232, v232, v232 quad_perm:[2,3,0,1] row_mask:0xf bank_mask:0xf
	v_add_f32_dpp v233, v233, v233 quad_perm:[2,3,0,1] row_mask:0xf bank_mask:0xf
	s_nop 0
	v_add_f32_dpp v232, v232, v232 row_half_mirror row_mask:0xf bank_mask:0xf
	v_add_f32_dpp v233, v233, v233 row_half_mirror row_mask:0xf bank_mask:0xf
	s_nop 0
	s_lshl_b64 s[18:19], s[38:39], 6
	v_cndmask_b32_e64 v149, v149, v232, s[18:19]
	v_cndmask_b32_e64 v150, v150, v233, s[18:19]
	ds_write_b128 v152, v[4:7]
	ds_write_b128 v152, v[0:3] offset:16
	ds_read_b128 v[130:133], v153
	ds_read_b128 v[176:179], v153 offset:1152
	s_waitcnt lgkmcnt(4)
	s_waitcnt vmcnt(22)
	v_add_u32_e32 v170, 0x50000, v239
	v_add_u32_e32 v171, 0x54000, v239
	global_store_dwordx4 v170, v[208:211], s[68:69]
	global_store_dwordx4 v171, v[212:215], s[68:69]
	v_pk_add_f32 v[240:241], v[240:241], v[192:193]
	v_pk_add_f32 v[242:243], v[242:243], v[194:195]
	v_pk_add_f32 v[244:245], v[244:245], v[196:197]
	v_pk_add_f32 v[246:247], v[246:247], v[198:199]
	v_add_u32_e32 v180, 0xb0000, v144
	v_add_u32_e32 v181, 0xb8000, v144
	global_store_dwordx4 v180, v[240:243], s[72:73]
	global_store_dwordx4 v181, v[244:247], s[72:73]
	v_mul_f32_e32 v232, v240, v240
	v_fmac_f32_e32 v232, v241, v241
	v_fmac_f32_e32 v232, v242, v242
	v_fmac_f32_e32 v232, v243, v243
	v_mul_f32_e32 v233, v244, v244
	v_fmac_f32_e32 v233, v245, v245
	v_fmac_f32_e32 v233, v246, v246
	v_fmac_f32_e32 v233, v247, v247
	v_pk_mul_f32 v[248:249], v[240:241], v[224:225]
	v_pk_mul_f32 v[242:243], v[242:243], v[226:227]
	v_cvt_pk_bf16_f32 v216, v248, v249
	v_cvt_pk_bf16_f32 v217, v242, v243
	v_pk_mul_f32 v[248:249], v[244:245], v[224:225]
	v_pk_mul_f32 v[246:247], v[246:247], v[226:227]
	v_cvt_pk_bf16_f32 v218, v248, v249
	v_cvt_pk_bf16_f32 v219, v246, v247
	s_waitcnt lgkmcnt(0)
	s_waitcnt vmcnt(24)
	v_pk_add_f32 v[130:131], v[130:131], v[76:77]
	v_pk_add_f32 v[132:133], v[132:133], v[78:79]
	v_pk_add_f32 v[176:177], v[176:177], v[72:73]
	v_pk_add_f32 v[178:179], v[178:179], v[74:75]
	v_add_u32_e32 v180, 0xb0200, v144
	v_add_u32_e32 v181, 0xb8200, v144
	global_store_dwordx4 v180, v[130:133], s[72:73]
	global_store_dwordx4 v181, v[176:179], s[72:73]
	v_fmac_f32_e32 v232, v130, v130
	v_fmac_f32_e32 v232, v131, v131
	v_fmac_f32_e32 v232, v132, v132
	v_fmac_f32_e32 v232, v133, v133
	v_fmac_f32_e32 v233, v176, v176
	v_fmac_f32_e32 v233, v177, v177
	v_fmac_f32_e32 v233, v178, v178
	v_fmac_f32_e32 v233, v179, v179
	v_pk_mul_f32 v[248:249], v[130:131], v[228:229]
	v_pk_mul_f32 v[132:133], v[132:133], v[230:231]
	v_cvt_pk_bf16_f32 v220, v248, v249
	v_cvt_pk_bf16_f32 v221, v132, v133
	v_pk_mul_f32 v[248:249], v[176:177], v[228:229]
	v_pk_mul_f32 v[178:179], v[178:179], v[230:231]
	v_cvt_pk_bf16_f32 v222, v248, v249
	v_cvt_pk_bf16_f32 v223, v178, v179
	ds_write_b64 v234, v[216:217]
	ds_write_b64 v234, v[220:221] offset:64
	ds_write_b64 v234, v[218:219] offset:1152
	ds_write_b64 v234, v[222:223] offset:1216
	ds_read_b128 v[208:211], v153
	ds_read_b128 v[212:215], v153 offset:1152
	s_nop 0
	v_add_f32_dpp v232, v232, v232 quad_perm:[1,0,3,2] row_mask:0xf bank_mask:0xf
	v_add_f32_dpp v233, v233, v233 quad_perm:[1,0,3,2] row_mask:0xf bank_mask:0xf
	s_nop 0
	v_add_f32_dpp v232, v232, v232 quad_perm:[2,3,0,1] row_mask:0xf bank_mask:0xf
	v_add_f32_dpp v233, v233, v233 quad_perm:[2,3,0,1] row_mask:0xf bank_mask:0xf
	s_nop 0
	v_add_f32_dpp v232, v232, v232 row_half_mirror row_mask:0xf bank_mask:0xf
	v_add_f32_dpp v233, v233, v233 row_half_mirror row_mask:0xf bank_mask:0xf
	s_nop 0
	s_lshl_b64 s[18:19], s[38:39], 7
	v_cndmask_b32_e64 v149, v149, v232, s[18:19]
	v_cndmask_b32_e64 v150, v150, v233, s[18:19]
	s_waitcnt lgkmcnt(0)
	v_add_u32_e32 v170, 0x58000, v239
	v_add_u32_e32 v171, 0x5c000, v239
	global_store_dwordx4 v170, v[208:211], s[68:69]
	global_store_dwordx4 v171, v[212:215], s[68:69]
	v_and_b32_e32 v145, 7, v189
	v_lshrrev_b32_e32 v146, 2, v145
	v_and_b32_e32 v145, 3, v145
	v_lshlrev_b32_e32 v146, 13, v146
	v_lshl_add_u32 v145, v145, 10, v146
	v_add_u32_e32 v145, v145, v238
	global_store_dword v145, v149, s[68:69]
	global_store_dword v145, v150, s[68:69] offset:512
	s_branch .Lres_join
